# attention: K/V staging LDS writes moved from step end to mid-step (before first PV MFMA), off the barrier critical path
# speedup vs baseline: 1.0307x; 1.0017x over previous
; __device__ __forceinline__ void attn_unit(LAS unsigned char* lds, const bf16_t* Qrow0, int nqw, int limbase, bool prompt, size_t kv0, int NT, int h,
;                                           const bf16_t* KN, const bf16_t* KR, const bf16_t* VVt, bf16_t* Yrow0, unsigned* tkctr, int& tick) {
;     ...
;     for (int t = 0; t < NT; t += 2) {
;         ATT_ITER(t, ak0, ak1, av, bk0, bk1, bv);
;         if (t + 1 < NT) ATT_ITER(t + 1, bk0, bk1, bv, ak0, ak1, av);
;     }
.Latt_barB:
	s_waitcnt lgkmcnt(0)
	s_barrier
	s_add_i32 s73, s73, 2
	s_cmp_ge_i32 s75, s74
	s_cbranch_scc1 .LBB0_960

.Latt_barA:
	s_waitcnt lgkmcnt(0)
	s_barrier
	s_cmp_ge_i32 s40, s74
	s_cbranch_scc1 .LBB0_953
	s_min_i32 s40, s73, s33
	v_mad_u64_u32 v[2:3], s[10:11], v196, s40, 0
	v_lshl_add_u64 v[2:3], v[2:3], 1, v[192:193]
	s_mov_b32 s67, s41
	global_load_dwordx4 v[168:171], v[2:3], off
	v_mad_u64_u32 v[2:3], s[10:11], v195, s40, 0
	v_lshl_add_u64 v[2:3], v[2:3], 1, v[202:203]
	s_lshl_b64 s[10:11], s[66:67], 7
	global_load_dwordx4 v[172:175], v[2:3], off
	v_lshl_add_u64 v[2:3], v[200:201], 0, s[10:11]
	global_load_dwordx4 v[176:179], v[2:3], off
	s_cmp_ge_i32 s75, s72
	s_mov_b64 s[10:11], -1
	s_cbranch_scc1 .LBB0_954
	s_andn2_b64 vcc, exec, s[10:11]
	s_cbranch_vccz .LBB0_957

; #define LAS __attribute__((address_space(3)))
; template <bool QK, bool SM>
; __device__ __forceinline__ void attn_step(const LAS unsigned char* kb, const LAS unsigned char* vbp, const bf16x8 (&qr)[6],
;                                           f32x16& s0, f32x16& s1, f32x16& o0, f32x16& o1, float& mrow, float& lsum) {
;     ...
;         for (int s = 0; s < 6; ++s) { const bf16x8 ka = *(const LAS bf16x8*)(kb + s * 32), kc = *(const LAS bf16x8*)(kb + 32 * KPITCH + s * 32);
;             n0 = __builtin_amdgcn_mfma_f32_32x32x16_bf16(ka, qr[s], n0, 0, 0, 0); n1 = __builtin_amdgcn_mfma_f32_32x32x16_bf16(kc, qr[s], n1, 0, 0, 0); }
;     ...
;         for (int r = 0; r < 16; r += 2) { f32x2 a = (f32x2){s0[r], s0[r + 1]} - m2, b = (f32x2){s1[r], s1[r + 1]} - m2;
;             a.x = __builtin_amdgcn_exp2f(a.x); a.y = __builtin_amdgcn_exp2f(a.y); b.x = __builtin_amdgcn_exp2f(b.x); b.y = __builtin_amdgcn_exp2f(b.y);
;             s0[r] = a.x; s0[r + 1] = a.y; s1[r] = b.x; s1[r + 1] = b.y; ps2 += a + b; }
.Latt_contA:
	v_mfma_f32_32x32x16_bf16 v[80:95], v[80:83], v[164:167], v[218:233]
	v_exp_f32_e32 v128, v48
	v_exp_f32_e32 v129, v49
	v_exp_f32_e32 v48, v16
	v_exp_f32_e32 v49, v17
	v_exp_f32_e32 v130, v50
	v_mfma_f32_32x32x16_bf16 v[80:95], v[96:99], v[160:163], v[80:95]
	v_exp_f32_e32 v131, v51
	v_exp_f32_e32 v50, v18
	v_exp_f32_e32 v51, v19
	v_add_f32_e32 v10, v128, v48
	v_add_f32_e32 v11, v129, v49
	v_add_f32_e32 v10, 0, v10
	v_add_f32_e32 v11, 0, v11
	v_add_f32_e32 v12, v130, v50
	v_add_f32_e32 v13, v131, v51
	v_mfma_f32_32x32x16_bf16 v[80:95], v[100:103], v[156:159], v[80:95]
	v_add_u32_e32 v100, v214, v204
	v_add_f32_e32 v10, v12, v10
	v_add_f32_e32 v11, v13, v11
	v_mfma_f32_32x32x16_bf16 v[80:95], v[104:107], v[152:155], v[80:95]
	v_exp_f32_e32 v12, v52
	v_exp_f32_e32 v13, v53
	v_exp_f32_e32 v16, v54
	v_exp_f32_e32 v17, v55

; __device__ __forceinline__ unsigned cvt_pk_bf16(float lo, float hi) { unsigned r; asm("v_cvt_pk_bf16_f32 %0, %1, %2" : "=v"(r) : "v"(lo), "v"(hi)); return r; }
; template <bool QK, bool SM>
; __device__ __forceinline__ void attn_step(const LAS unsigned char* kb, const LAS unsigned char* vbp, const bf16x8 (&qr)[6],
;                                           f32x16& s0, f32x16& s1, f32x16& o0, f32x16& o1, float& mrow, float& lsum) {
;     ...
;         for (int S = 0; S < 4; ++S) { u32x4 w;
;             if (S < 2) { w.x = cvt_pk_bf16(s0[8 * S + 0], s0[8 * S + 1]); w.y = cvt_pk_bf16(s0[8 * S + 2], s0[8 * S + 3]); w.z = cvt_pk_bf16(s0[8 * S + 4], s0[8 * S + 5]); w.w = cvt_pk_bf16(s0[8 * S + 6], s0[8 * S + 7]); }
;             else { w.x = cvt_pk_bf16(s1[8 * S - 16], s1[8 * S - 15]); w.y = cvt_pk_bf16(s1[8 * S - 14], s1[8 * S - 13]); w.z = cvt_pk_bf16(s1[8 * S - 12], s1[8 * S - 11]); w.w = cvt_pk_bf16(s1[8 * S - 10], s1[8 * S - 9]); }
;             pb[S] = __builtin_bit_cast(bf16x8, w); }
	v_cvt_pk_bf16_f32 v96, v128, v129

; #define LAS __attribute__((address_space(3)))
; template <bool QK, bool SM>
; __device__ __forceinline__ void attn_step(const LAS unsigned char* kb, const LAS unsigned char* vbp, const bf16x8 (&qr)[6],
;                                           f32x16& s0, f32x16& s1, f32x16& o0, f32x16& o1, float& mrow, float& lsum) {
;     ...
;         for (int s = 0; s < 6; ++s) { const bf16x8 ka = *(const LAS bf16x8*)(kb + s * 32), kc = *(const LAS bf16x8*)(kb + 32 * KPITCH + s * 32);
;             n0 = __builtin_amdgcn_mfma_f32_32x32x16_bf16(ka, qr[s], n0, 0, 0, 0); n1 = __builtin_amdgcn_mfma_f32_32x32x16_bf16(kc, qr[s], n1, 0, 0, 0); }
;     ...
;             const u32x2 a0 = *(const LAS u32x2*)(vbp + S * 32), a1 = *(const LAS u32x2*)(vbp + S * 32 + 16);
;             const u32x2 c0 = *(const LAS u32x2*)(vbp + 32 * VPITCH + S * 32), c1 = *(const LAS u32x2*)(vbp + 32 * VPITCH + S * 32 + 16);
	s_waitcnt lgkmcnt(2)
	v_mfma_f32_32x32x16_bf16 v[112:127], v[108:111], v[144:147], v[112:127]
	v_add_u32_e32 v110, 0x6800, v100
	v_add_u32_e32 v111, 0x7800, v100
	ds_read2_b64 v[100:103], v111 offset0:32 offset1:34

; __device__ __forceinline__ unsigned cvt_pk_bf16(float lo, float hi) { unsigned r; asm("v_cvt_pk_bf16_f32 %0, %1, %2" : "=v"(r) : "v"(lo), "v"(hi)); return r; }
; template <bool QK, bool SM>
; __device__ __forceinline__ void attn_step(const LAS unsigned char* kb, const LAS unsigned char* vbp, const bf16x8 (&qr)[6],
;                                           f32x16& s0, f32x16& s1, f32x16& o0, f32x16& o1, float& mrow, float& lsum) {
;     ...
;         for (int S = 0; S < 4; ++S) { u32x4 w;
;             if (S < 2) { w.x = cvt_pk_bf16(s0[8 * S + 0], s0[8 * S + 1]); w.y = cvt_pk_bf16(s0[8 * S + 2], s0[8 * S + 3]); w.z = cvt_pk_bf16(s0[8 * S + 4], s0[8 * S + 5]); w.w = cvt_pk_bf16(s0[8 * S + 6], s0[8 * S + 7]); }
;             else { w.x = cvt_pk_bf16(s1[8 * S - 16], s1[8 * S - 15]); w.y = cvt_pk_bf16(s1[8 * S - 14], s1[8 * S - 13]); w.z = cvt_pk_bf16(s1[8 * S - 12], s1[8 * S - 11]); w.w = cvt_pk_bf16(s1[8 * S - 10], s1[8 * S - 9]); }
;             pb[S] = __builtin_bit_cast(bf16x8, w); }
	v_cvt_pk_bf16_f32 v97, v130, v131


; __device__ __forceinline__ unsigned cvt_pk_bf16(float lo, float hi) { unsigned r; asm("v_cvt_pk_bf16_f32 %0, %1, %2" : "=v"(r) : "v"(lo), "v"(hi)); return r; }
; template <bool QK, bool SM>
; __device__ __forceinline__ void attn_step(const LAS unsigned char* kb, const LAS unsigned char* vbp, const bf16x8 (&qr)[6],
;                                           f32x16& s0, f32x16& s1, f32x16& o0, f32x16& o1, float& mrow, float& lsum) {
;     ...
;         for (int S = 0; S < 4; ++S) { u32x4 w;
;             if (S < 2) { w.x = cvt_pk_bf16(s0[8 * S + 0], s0[8 * S + 1]); w.y = cvt_pk_bf16(s0[8 * S + 2], s0[8 * S + 3]); w.z = cvt_pk_bf16(s0[8 * S + 4], s0[8 * S + 5]); w.w = cvt_pk_bf16(s0[8 * S + 6], s0[8 * S + 7]); }
;             else { w.x = cvt_pk_bf16(s1[8 * S - 16], s1[8 * S - 15]); w.y = cvt_pk_bf16(s1[8 * S - 14], s1[8 * S - 13]); w.z = cvt_pk_bf16(s1[8 * S - 12], s1[8 * S - 11]); w.w = cvt_pk_bf16(s1[8 * S - 10], s1[8 * S - 9]); }
;             pb[S] = __builtin_bit_cast(bf16x8, w); }
	v_cvt_pk_bf16_f32 v98, v12, v13

; #define LAS __attribute__((address_space(3)))
; template <bool QK, bool SM>
; __device__ __forceinline__ void attn_step(const LAS unsigned char* kb, const LAS unsigned char* vbp, const bf16x8 (&qr)[6],
;                                           f32x16& s0, f32x16& s1, f32x16& o0, f32x16& o1, float& mrow, float& lsum) {
;     ...
;         for (int s = 0; s < 6; ++s) { const bf16x8 ka = *(const LAS bf16x8*)(kb + s * 32), kc = *(const LAS bf16x8*)(kb + 32 * KPITCH + s * 32);
;             n0 = __builtin_amdgcn_mfma_f32_32x32x16_bf16(ka, qr[s], n0, 0, 0, 0); n1 = __builtin_amdgcn_mfma_f32_32x32x16_bf16(kc, qr[s], n1, 0, 0, 0); }
;     ...
;             const u32x2 a0 = *(const LAS u32x2*)(vbp + S * 32), a1 = *(const LAS u32x2*)(vbp + S * 32 + 16);
	s_waitcnt lgkmcnt(2)
	v_mfma_f32_32x32x16_bf16 v[80:95], v[6:9], v[148:151], v[80:95]
	ds_read2_b64 v[6:9], v110 offset1:2

; __device__ __forceinline__ unsigned cvt_pk_bf16(float lo, float hi) { unsigned r; asm("v_cvt_pk_bf16_f32 %0, %1, %2" : "=v"(r) : "v"(lo), "v"(hi)); return r; }
; template <bool QK, bool SM>
; __device__ __forceinline__ void attn_step(const LAS unsigned char* kb, const LAS unsigned char* vbp, const bf16x8 (&qr)[6],
;                                           f32x16& s0, f32x16& s1, f32x16& o0, f32x16& o1, float& mrow, float& lsum) {
;     ...
;         for (int S = 0; S < 4; ++S) { u32x4 w;
;             if (S < 2) { w.x = cvt_pk_bf16(s0[8 * S + 0], s0[8 * S + 1]); w.y = cvt_pk_bf16(s0[8 * S + 2], s0[8 * S + 3]); w.z = cvt_pk_bf16(s0[8 * S + 4], s0[8 * S + 5]); w.w = cvt_pk_bf16(s0[8 * S + 6], s0[8 * S + 7]); }
;             else { w.x = cvt_pk_bf16(s1[8 * S - 16], s1[8 * S - 15]); w.y = cvt_pk_bf16(s1[8 * S - 14], s1[8 * S - 13]); w.z = cvt_pk_bf16(s1[8 * S - 12], s1[8 * S - 11]); w.w = cvt_pk_bf16(s1[8 * S - 10], s1[8 * S - 9]); }
;             pb[S] = __builtin_bit_cast(bf16x8, w); }
	v_cvt_pk_bf16_f32 v99, v16, v17

; #define LAS __attribute__((address_space(3)))
; template <bool QK, bool SM>
; __device__ __forceinline__ void attn_step(const LAS unsigned char* kb, const LAS unsigned char* vbp, const bf16x8 (&qr)[6],
;                                           f32x16& s0, f32x16& s1, f32x16& o0, f32x16& o1, float& mrow, float& lsum) {
;     ...
;         for (int S = 0; S < 4; ++S) {
;             const u32x2 a0 = *(const LAS u32x2*)(vbp + S * 32), a1 = *(const LAS u32x2*)(vbp + S * 32 + 16);
;             const u32x2 c0 = *(const LAS u32x2*)(vbp + 32 * VPITCH + S * 32), c1 = *(const LAS u32x2*)(vbp + 32 * VPITCH + S * 32 + 16);
;             const bf16x8 va = __builtin_bit_cast(bf16x8, (u32x4){a0.x, a0.y, a1.x, a1.y}), vc = __builtin_bit_cast(bf16x8, (u32x4){c0.x, c0.y, c1.x, c1.y});
;             o0 = __builtin_amdgcn_mfma_f32_32x32x16_bf16(va, pb[S], o0, 0, 0, 0); o1 = __builtin_amdgcn_mfma_f32_32x32x16_bf16(vc, pb[S], o1, 0, 0, 0); }
	s_waitcnt lgkmcnt(0)
	s_nop 0
	s_waitcnt vmcnt(5)
	ds_write_b128 v197, v[168:171]
	s_and_saveexec_b64 s[10:11], s[0:1]
	s_waitcnt vmcnt(4)
	ds_write_b128 v212, v[172:175]
	s_or_b64 exec, exec, s[10:11]
	v_add_u32_e32 v235, 0x8a00, v199
	s_waitcnt vmcnt(3)
	ds_write2_b64 v235, v[176:177], v[178:179] offset1:1
	v_mfma_f32_32x32x16_bf16 v[32:47], v[6:9], v[96:99], v[32:47]
	ds_read2_b64 v[6:9], v110 offset0:4 offset1:6
	v_mov_b32_e32 v14, v20
	v_mov_b32_e32 v15, v21
	v_mfma_f32_32x32x16_bf16 v[64:79], v[100:103], v[96:99], v[64:79]
	ds_read2_b64 v[100:103], v111 offset0:36 offset1:38
	v_exp_f32_e32 v18, v56
	v_exp_f32_e32 v19, v57
	v_exp_f32_e32 v20, v58
	v_exp_f32_e32 v21, v59
	v_exp_f32_e32 v52, v60
	v_exp_f32_e32 v53, v61
	v_exp_f32_e32 v104, v62
	v_exp_f32_e32 v105, v63

; __device__ __forceinline__ unsigned cvt_pk_bf16(float lo, float hi) { unsigned r; asm("v_cvt_pk_bf16_f32 %0, %1, %2" : "=v"(r) : "v"(lo), "v"(hi)); return r; }
; template <bool QK, bool SM>
; __device__ __forceinline__ void attn_step(const LAS unsigned char* kb, const LAS unsigned char* vbp, const bf16x8 (&qr)[6],
;                                           f32x16& s0, f32x16& s1, f32x16& o0, f32x16& o1, float& mrow, float& lsum) {
;     ...
;         for (int S = 0; S < 4; ++S) { u32x4 w;
;             if (S < 2) { w.x = cvt_pk_bf16(s0[8 * S + 0], s0[8 * S + 1]); w.y = cvt_pk_bf16(s0[8 * S + 2], s0[8 * S + 3]); w.z = cvt_pk_bf16(s0[8 * S + 4], s0[8 * S + 5]); w.w = cvt_pk_bf16(s0[8 * S + 6], s0[8 * S + 7]); }
;             else { w.x = cvt_pk_bf16(s1[8 * S - 16], s1[8 * S - 15]); w.y = cvt_pk_bf16(s1[8 * S - 14], s1[8 * S - 13]); w.z = cvt_pk_bf16(s1[8 * S - 12], s1[8 * S - 11]); w.w = cvt_pk_bf16(s1[8 * S - 10], s1[8 * S - 9]); }
;             pb[S] = __builtin_bit_cast(bf16x8, w); }
	v_cvt_pk_bf16_f32 v96, v18, v19


; __device__ __forceinline__ unsigned cvt_pk_bf16(float lo, float hi) { unsigned r; asm("v_cvt_pk_bf16_f32 %0, %1, %2" : "=v"(r) : "v"(lo), "v"(hi)); return r; }
; template <bool QK, bool SM>
; __device__ __forceinline__ void attn_step(const LAS unsigned char* kb, const LAS unsigned char* vbp, const bf16x8 (&qr)[6],
;                                           f32x16& s0, f32x16& s1, f32x16& o0, f32x16& o1, float& mrow, float& lsum) {
;     ...
;         for (int S = 0; S < 4; ++S) { u32x4 w;
;             if (S < 2) { w.x = cvt_pk_bf16(s0[8 * S + 0], s0[8 * S + 1]); w.y = cvt_pk_bf16(s0[8 * S + 2], s0[8 * S + 3]); w.z = cvt_pk_bf16(s0[8 * S + 4], s0[8 * S + 5]); w.w = cvt_pk_bf16(s0[8 * S + 6], s0[8 * S + 7]); }
;             else { w.x = cvt_pk_bf16(s1[8 * S - 16], s1[8 * S - 15]); w.y = cvt_pk_bf16(s1[8 * S - 14], s1[8 * S - 13]); w.z = cvt_pk_bf16(s1[8 * S - 12], s1[8 * S - 11]); w.w = cvt_pk_bf16(s1[8 * S - 10], s1[8 * S - 9]); }
;             pb[S] = __builtin_bit_cast(bf16x8, w); }
	v_cvt_pk_bf16_f32 v97, v20, v21


; __device__ __forceinline__ unsigned cvt_pk_bf16(float lo, float hi) { unsigned r; asm("v_cvt_pk_bf16_f32 %0, %1, %2" : "=v"(r) : "v"(lo), "v"(hi)); return r; }
; template <bool QK, bool SM>
; __device__ __forceinline__ void attn_step(const LAS unsigned char* kb, const LAS unsigned char* vbp, const bf16x8 (&qr)[6],
;                                           f32x16& s0, f32x16& s1, f32x16& o0, f32x16& o1, float& mrow, float& lsum) {
;     ...
;         for (int S = 0; S < 4; ++S) { u32x4 w;
;             if (S < 2) { w.x = cvt_pk_bf16(s0[8 * S + 0], s0[8 * S + 1]); w.y = cvt_pk_bf16(s0[8 * S + 2], s0[8 * S + 3]); w.z = cvt_pk_bf16(s0[8 * S + 4], s0[8 * S + 5]); w.w = cvt_pk_bf16(s0[8 * S + 6], s0[8 * S + 7]); }
;             else { w.x = cvt_pk_bf16(s1[8 * S - 16], s1[8 * S - 15]); w.y = cvt_pk_bf16(s1[8 * S - 14], s1[8 * S - 13]); w.z = cvt_pk_bf16(s1[8 * S - 12], s1[8 * S - 11]); w.w = cvt_pk_bf16(s1[8 * S - 10], s1[8 * S - 9]); }
;             pb[S] = __builtin_bit_cast(bf16x8, w); }
	v_cvt_pk_bf16_f32 v98, v52, v53


; __device__ __forceinline__ unsigned cvt_pk_bf16(float lo, float hi) { unsigned r; asm("v_cvt_pk_bf16_f32 %0, %1, %2" : "=v"(r) : "v"(lo), "v"(hi)); return r; }
; template <bool QK, bool SM>
; __device__ __forceinline__ void attn_step(const LAS unsigned char* kb, const LAS unsigned char* vbp, const bf16x8 (&qr)[6],
;                                           f32x16& s0, f32x16& s1, f32x16& o0, f32x16& o1, float& mrow, float& lsum) {
;     ...
;         for (int S = 0; S < 4; ++S) { u32x4 w;
;             if (S < 2) { w.x = cvt_pk_bf16(s0[8 * S + 0], s0[8 * S + 1]); w.y = cvt_pk_bf16(s0[8 * S + 2], s0[8 * S + 3]); w.z = cvt_pk_bf16(s0[8 * S + 4], s0[8 * S + 5]); w.w = cvt_pk_bf16(s0[8 * S + 6], s0[8 * S + 7]); }
;             else { w.x = cvt_pk_bf16(s1[8 * S - 16], s1[8 * S - 15]); w.y = cvt_pk_bf16(s1[8 * S - 14], s1[8 * S - 13]); w.z = cvt_pk_bf16(s1[8 * S - 12], s1[8 * S - 11]); w.w = cvt_pk_bf16(s1[8 * S - 10], s1[8 * S - 9]); }
;             pb[S] = __builtin_bit_cast(bf16x8, w); }
	v_cvt_pk_bf16_f32 v99, v104, v105

; #define LAS __attribute__((address_space(3)))
; template <bool QK, bool SM>
; __device__ __forceinline__ void attn_step(const LAS unsigned char* kb, const LAS unsigned char* vbp, const bf16x8 (&qr)[6],
;                                           f32x16& s0, f32x16& s1, f32x16& o0, f32x16& o1, float& mrow, float& lsum) {
;     ...
;             a.x = __builtin_amdgcn_exp2f(a.x); a.y = __builtin_amdgcn_exp2f(a.y); b.x = __builtin_amdgcn_exp2f(b.x); b.y = __builtin_amdgcn_exp2f(b.y);
;     ...
;         for (int S = 0; S < 4; ++S) {
;             const u32x2 a0 = *(const LAS u32x2*)(vbp + S * 32), a1 = *(const LAS u32x2*)(vbp + S * 32 + 16);
;             const u32x2 c0 = *(const LAS u32x2*)(vbp + 32 * VPITCH + S * 32), c1 = *(const LAS u32x2*)(vbp + 32 * VPITCH + S * 32 + 16);
;             const bf16x8 va = __builtin_bit_cast(bf16x8, (u32x4){a0.x, a0.y, a1.x, a1.y}), vc = __builtin_bit_cast(bf16x8, (u32x4){c0.x, c0.y, c1.x, c1.y});
;             o0 = __builtin_amdgcn_mfma_f32_32x32x16_bf16(va, pb[S], o0, 0, 0, 0); o1 = __builtin_amdgcn_mfma_f32_32x32x16_bf16(vc, pb[S], o1, 0, 0, 0); }
	v_exp_f32_e32 v14, v14
	s_waitcnt lgkmcnt(1)
	v_mfma_f32_32x32x16_bf16 v[32:47], v[6:9], v[96:99], v[32:47]
	v_exp_f32_e32 v106, v22
	v_exp_f32_e32 v107, v23
	ds_read2_b64 v[6:9], v110 offset0:8 offset1:10
	v_exp_f32_e32 v15, v15
	v_exp_f32_e32 v108, v24
	s_waitcnt lgkmcnt(1)
	v_mfma_f32_32x32x16_bf16 v[64:79], v[100:103], v[96:99], v[64:79]
	ds_read2_b64 v[96:99], v111 offset0:40 offset1:42
	v_exp_f32_e32 v109, v25

; __device__ __forceinline__ unsigned cvt_pk_bf16(float lo, float hi) { unsigned r; asm("v_cvt_pk_bf16_f32 %0, %1, %2" : "=v"(r) : "v"(lo), "v"(hi)); return r; }
; template <bool QK, bool SM>
; __device__ __forceinline__ void attn_step(const LAS unsigned char* kb, const LAS unsigned char* vbp, const bf16x8 (&qr)[6],
;                                           f32x16& s0, f32x16& s1, f32x16& o0, f32x16& o1, float& mrow, float& lsum) {
;     ...
;         for (int S = 0; S < 4; ++S) { u32x4 w;
;             if (S < 2) { w.x = cvt_pk_bf16(s0[8 * S + 0], s0[8 * S + 1]); w.y = cvt_pk_bf16(s0[8 * S + 2], s0[8 * S + 3]); w.z = cvt_pk_bf16(s0[8 * S + 4], s0[8 * S + 5]); w.w = cvt_pk_bf16(s0[8 * S + 6], s0[8 * S + 7]); }
;             else { w.x = cvt_pk_bf16(s1[8 * S - 16], s1[8 * S - 15]); w.y = cvt_pk_bf16(s1[8 * S - 14], s1[8 * S - 13]); w.z = cvt_pk_bf16(s1[8 * S - 12], s1[8 * S - 11]); w.w = cvt_pk_bf16(s1[8 * S - 10], s1[8 * S - 9]); }
;             pb[S] = __builtin_bit_cast(bf16x8, w); }
	v_cvt_pk_bf16_f32 v22, v48, v49


; __device__ __forceinline__ unsigned cvt_pk_bf16(float lo, float hi) { unsigned r; asm("v_cvt_pk_bf16_f32 %0, %1, %2" : "=v"(r) : "v"(lo), "v"(hi)); return r; }
; template <bool QK, bool SM>
; __device__ __forceinline__ void attn_step(const LAS unsigned char* kb, const LAS unsigned char* vbp, const bf16x8 (&qr)[6],
;                                           f32x16& s0, f32x16& s1, f32x16& o0, f32x16& o1, float& mrow, float& lsum) {
;     ...
;         for (int S = 0; S < 4; ++S) { u32x4 w;
;             if (S < 2) { w.x = cvt_pk_bf16(s0[8 * S + 0], s0[8 * S + 1]); w.y = cvt_pk_bf16(s0[8 * S + 2], s0[8 * S + 3]); w.z = cvt_pk_bf16(s0[8 * S + 4], s0[8 * S + 5]); w.w = cvt_pk_bf16(s0[8 * S + 6], s0[8 * S + 7]); }
;             else { w.x = cvt_pk_bf16(s1[8 * S - 16], s1[8 * S - 15]); w.y = cvt_pk_bf16(s1[8 * S - 14], s1[8 * S - 13]); w.z = cvt_pk_bf16(s1[8 * S - 12], s1[8 * S - 11]); w.w = cvt_pk_bf16(s1[8 * S - 10], s1[8 * S - 9]); }
;             pb[S] = __builtin_bit_cast(bf16x8, w); }
	v_cvt_pk_bf16_f32 v23, v50, v51


; __device__ __forceinline__ unsigned cvt_pk_bf16(float lo, float hi) { unsigned r; asm("v_cvt_pk_bf16_f32 %0, %1, %2" : "=v"(r) : "v"(lo), "v"(hi)); return r; }
; template <bool QK, bool SM>
; __device__ __forceinline__ void attn_step(const LAS unsigned char* kb, const LAS unsigned char* vbp, const bf16x8 (&qr)[6],
;                                           f32x16& s0, f32x16& s1, f32x16& o0, f32x16& o1, float& mrow, float& lsum) {
;     ...
;         for (int S = 0; S < 4; ++S) { u32x4 w;
;             if (S < 2) { w.x = cvt_pk_bf16(s0[8 * S + 0], s0[8 * S + 1]); w.y = cvt_pk_bf16(s0[8 * S + 2], s0[8 * S + 3]); w.z = cvt_pk_bf16(s0[8 * S + 4], s0[8 * S + 5]); w.w = cvt_pk_bf16(s0[8 * S + 6], s0[8 * S + 7]); }
;             else { w.x = cvt_pk_bf16(s1[8 * S - 16], s1[8 * S - 15]); w.y = cvt_pk_bf16(s1[8 * S - 14], s1[8 * S - 13]); w.z = cvt_pk_bf16(s1[8 * S - 12], s1[8 * S - 11]); w.w = cvt_pk_bf16(s1[8 * S - 10], s1[8 * S - 9]); }
;             pb[S] = __builtin_bit_cast(bf16x8, w); }
	v_cvt_pk_bf16_f32 v24, v14, v15


; __device__ __forceinline__ unsigned cvt_pk_bf16(float lo, float hi) { unsigned r; asm("v_cvt_pk_bf16_f32 %0, %1, %2" : "=v"(r) : "v"(lo), "v"(hi)); return r; }
; template <bool QK, bool SM>
; __device__ __forceinline__ void attn_step(const LAS unsigned char* kb, const LAS unsigned char* vbp, const bf16x8 (&qr)[6],
;                                           f32x16& s0, f32x16& s1, f32x16& o0, f32x16& o1, float& mrow, float& lsum) {
;     ...
;         for (int S = 0; S < 4; ++S) { u32x4 w;
;             if (S < 2) { w.x = cvt_pk_bf16(s0[8 * S + 0], s0[8 * S + 1]); w.y = cvt_pk_bf16(s0[8 * S + 2], s0[8 * S + 3]); w.z = cvt_pk_bf16(s0[8 * S + 4], s0[8 * S + 5]); w.w = cvt_pk_bf16(s0[8 * S + 6], s0[8 * S + 7]); }
;             else { w.x = cvt_pk_bf16(s1[8 * S - 16], s1[8 * S - 15]); w.y = cvt_pk_bf16(s1[8 * S - 14], s1[8 * S - 13]); w.z = cvt_pk_bf16(s1[8 * S - 12], s1[8 * S - 11]); w.w = cvt_pk_bf16(s1[8 * S - 10], s1[8 * S - 9]); }
;             pb[S] = __builtin_bit_cast(bf16x8, w); }
	v_cvt_pk_bf16_f32 v25, v106, v107

; #define LAS __attribute__((address_space(3)))
; template <bool QK, bool SM>
; __device__ __forceinline__ void attn_step(const LAS unsigned char* kb, const LAS unsigned char* vbp, const bf16x8 (&qr)[6],
;                                           f32x16& s0, f32x16& s1, f32x16& o0, f32x16& o1, float& mrow, float& lsum) {
;     ...
;         for (int s = 0; s < 6; ++s) { const bf16x8 ka = *(const LAS bf16x8*)(kb + s * 32), kc = *(const LAS bf16x8*)(kb + 32 * KPITCH + s * 32);
;             n0 = __builtin_amdgcn_mfma_f32_32x32x16_bf16(ka, qr[s], n0, 0, 0, 0); n1 = __builtin_amdgcn_mfma_f32_32x32x16_bf16(kc, qr[s], n1, 0, 0, 0); }
;     ...
;         for (int S = 0; S < 4; ++S) {
;             const u32x2 a0 = *(const LAS u32x2*)(vbp + S * 32), a1 = *(const LAS u32x2*)(vbp + S * 32 + 16);
;             const u32x2 c0 = *(const LAS u32x2*)(vbp + 32 * VPITCH + S * 32), c1 = *(const LAS u32x2*)(vbp + 32 * VPITCH + S * 32 + 16);
;             const bf16x8 va = __builtin_bit_cast(bf16x8, (u32x4){a0.x, a0.y, a1.x, a1.y}), vc = __builtin_bit_cast(bf16x8, (u32x4){c0.x, c0.y, c1.x, c1.y});
;             o0 = __builtin_amdgcn_mfma_f32_32x32x16_bf16(va, pb[S], o0, 0, 0, 0); o1 = __builtin_amdgcn_mfma_f32_32x32x16_bf16(vc, pb[S], o1, 0, 0, 0); }
	v_mfma_f32_32x32x16_bf16 v[80:95], v[2:5], v[144:147], v[80:95]
	v_exp_f32_e32 v100, v26
	v_exp_f32_e32 v101, v27
	s_nop 0
	v_exp_f32_e32 v30, v30
	v_exp_f32_e32 v31, v31
	s_waitcnt lgkmcnt(1)
	v_mfma_f32_32x32x16_bf16 v[32:47], v[6:9], v[22:25], v[32:47]
	v_mov_b32_e32 v6, v28
	v_mov_b32_e32 v7, v29
	ds_read2_b64 v[26:29], v111 offset0:44 offset1:46
	v_exp_f32_e32 v102, v6
	v_exp_f32_e32 v103, v7
	ds_read2_b64 v[6:9], v110 offset0:12 offset1:14
	s_waitcnt lgkmcnt(2)
	v_mfma_f32_32x32x16_bf16 v[64:79], v[96:99], v[22:25], v[64:79]

; __device__ __forceinline__ unsigned cvt_pk_bf16(float lo, float hi) { unsigned r; asm("v_cvt_pk_bf16_f32 %0, %1, %2" : "=v"(r) : "v"(lo), "v"(hi)); return r; }
; template <bool QK, bool SM>
; __device__ __forceinline__ void attn_step(const LAS unsigned char* kb, const LAS unsigned char* vbp, const bf16x8 (&qr)[6],
;                                           f32x16& s0, f32x16& s1, f32x16& o0, f32x16& o1, float& mrow, float& lsum) {
;     ...
;         for (int S = 0; S < 4; ++S) { u32x4 w;
;             if (S < 2) { w.x = cvt_pk_bf16(s0[8 * S + 0], s0[8 * S + 1]); w.y = cvt_pk_bf16(s0[8 * S + 2], s0[8 * S + 3]); w.z = cvt_pk_bf16(s0[8 * S + 4], s0[8 * S + 5]); w.w = cvt_pk_bf16(s0[8 * S + 6], s0[8 * S + 7]); }
;             else { w.x = cvt_pk_bf16(s1[8 * S - 16], s1[8 * S - 15]); w.y = cvt_pk_bf16(s1[8 * S - 14], s1[8 * S - 13]); w.z = cvt_pk_bf16(s1[8 * S - 12], s1[8 * S - 11]); w.w = cvt_pk_bf16(s1[8 * S - 10], s1[8 * S - 9]); }
;             pb[S] = __builtin_bit_cast(bf16x8, w); }
	v_cvt_pk_bf16_f32 v22, v108, v109


; __device__ __forceinline__ unsigned cvt_pk_bf16(float lo, float hi) { unsigned r; asm("v_cvt_pk_bf16_f32 %0, %1, %2" : "=v"(r) : "v"(lo), "v"(hi)); return r; }
; template <bool QK, bool SM>
; __device__ __forceinline__ void attn_step(const LAS unsigned char* kb, const LAS unsigned char* vbp, const bf16x8 (&qr)[6],
;                                           f32x16& s0, f32x16& s1, f32x16& o0, f32x16& o1, float& mrow, float& lsum) {
;     ...
;         for (int S = 0; S < 4; ++S) { u32x4 w;
;             if (S < 2) { w.x = cvt_pk_bf16(s0[8 * S + 0], s0[8 * S + 1]); w.y = cvt_pk_bf16(s0[8 * S + 2], s0[8 * S + 3]); w.z = cvt_pk_bf16(s0[8 * S + 4], s0[8 * S + 5]); w.w = cvt_pk_bf16(s0[8 * S + 6], s0[8 * S + 7]); }
;             else { w.x = cvt_pk_bf16(s1[8 * S - 16], s1[8 * S - 15]); w.y = cvt_pk_bf16(s1[8 * S - 14], s1[8 * S - 13]); w.z = cvt_pk_bf16(s1[8 * S - 12], s1[8 * S - 11]); w.w = cvt_pk_bf16(s1[8 * S - 10], s1[8 * S - 9]); }
;             pb[S] = __builtin_bit_cast(bf16x8, w); }
	v_cvt_pk_bf16_f32 v23, v100, v101


; __device__ __forceinline__ unsigned cvt_pk_bf16(float lo, float hi) { unsigned r; asm("v_cvt_pk_bf16_f32 %0, %1, %2" : "=v"(r) : "v"(lo), "v"(hi)); return r; }
; template <bool QK, bool SM>
; __device__ __forceinline__ void attn_step(const LAS unsigned char* kb, const LAS unsigned char* vbp, const bf16x8 (&qr)[6],
;                                           f32x16& s0, f32x16& s1, f32x16& o0, f32x16& o1, float& mrow, float& lsum) {
;     ...
;         for (int S = 0; S < 4; ++S) { u32x4 w;
;             if (S < 2) { w.x = cvt_pk_bf16(s0[8 * S + 0], s0[8 * S + 1]); w.y = cvt_pk_bf16(s0[8 * S + 2], s0[8 * S + 3]); w.z = cvt_pk_bf16(s0[8 * S + 4], s0[8 * S + 5]); w.w = cvt_pk_bf16(s0[8 * S + 6], s0[8 * S + 7]); }
;             else { w.x = cvt_pk_bf16(s1[8 * S - 16], s1[8 * S - 15]); w.y = cvt_pk_bf16(s1[8 * S - 14], s1[8 * S - 13]); w.z = cvt_pk_bf16(s1[8 * S - 12], s1[8 * S - 11]); w.w = cvt_pk_bf16(s1[8 * S - 10], s1[8 * S - 9]); }
;             pb[S] = __builtin_bit_cast(bf16x8, w); }
	v_cvt_pk_bf16_f32 v24, v102, v103


; __device__ __forceinline__ unsigned cvt_pk_bf16(float lo, float hi) { unsigned r; asm("v_cvt_pk_bf16_f32 %0, %1, %2" : "=v"(r) : "v"(lo), "v"(hi)); return r; }
; template <bool QK, bool SM>
; __device__ __forceinline__ void attn_step(const LAS unsigned char* kb, const LAS unsigned char* vbp, const bf16x8 (&qr)[6],
;                                           f32x16& s0, f32x16& s1, f32x16& o0, f32x16& o1, float& mrow, float& lsum) {
;     ...
;         for (int S = 0; S < 4; ++S) { u32x4 w;
;             if (S < 2) { w.x = cvt_pk_bf16(s0[8 * S + 0], s0[8 * S + 1]); w.y = cvt_pk_bf16(s0[8 * S + 2], s0[8 * S + 3]); w.z = cvt_pk_bf16(s0[8 * S + 4], s0[8 * S + 5]); w.w = cvt_pk_bf16(s0[8 * S + 6], s0[8 * S + 7]); }
;             else { w.x = cvt_pk_bf16(s1[8 * S - 16], s1[8 * S - 15]); w.y = cvt_pk_bf16(s1[8 * S - 14], s1[8 * S - 13]); w.z = cvt_pk_bf16(s1[8 * S - 12], s1[8 * S - 11]); w.w = cvt_pk_bf16(s1[8 * S - 10], s1[8 * S - 9]); }
;             pb[S] = __builtin_bit_cast(bf16x8, w); }
	v_cvt_pk_bf16_f32 v25, v30, v31

; template <bool QK, bool SM>
; __device__ __forceinline__ void attn_step(const LAS unsigned char* kb, const LAS unsigned char* vbp, const bf16x8 (&qr)[6],
;                                           f32x16& s0, f32x16& s1, f32x16& o0, f32x16& o1, float& mrow, float& lsum) {
;     ...
;         const float mnew = fmaxf(mrow, mx), alpha = __builtin_amdgcn_exp2f(mrow - mnew); mrow = mnew;
;         const f32x2 m2 = (f32x2){mnew, mnew}; f32x2 ps2 = (f32x2){0.f, 0.f};
; #pragma unroll
;         for (int r = 0; r < 16; r += 2) { f32x2 a = (f32x2){s0[r], s0[r + 1]} - m2, b = (f32x2){s1[r], s1[r + 1]} - m2;
;             a.x = __builtin_amdgcn_exp2f(a.x); a.y = __builtin_amdgcn_exp2f(a.y); b.x = __builtin_amdgcn_exp2f(b.x); b.y = __builtin_amdgcn_exp2f(b.y);
;             s0[r] = a.x; s0[r + 1] = a.y; s1[r] = b.x; s1[r + 1] = b.y; ps2 += a + b; }
;         const float ps = ps2.x + ps2.y;
;         lsum = lsum * alpha + ps;
; #pragma unroll
;         for (int r = 0; r < 16; ++r) { o0[r] *= alpha; o1[r] *= alpha; }
	s_waitcnt lgkmcnt(0)
	s_nop 0
	v_mfma_f32_32x32x16_bf16 v[32:47], v[6:9], v[22:25], v[32:47]
	v_add_f32_e32 v6, v12, v14
	v_add_f32_e32 v7, v13, v15
	v_add_f32_e32 v8, v16, v106
	v_add_f32_e32 v9, v17, v107
	v_add_f32_e32 v6, v6, v10
	v_add_f32_e32 v7, v7, v11
	v_add_f32_e32 v6, v8, v6
	v_add_f32_e32 v7, v9, v7
	v_add_f32_e32 v8, v18, v108
	v_add_f32_e32 v9, v19, v109
	v_mfma_f32_32x32x16_bf16 v[64:79], v[26:29], v[22:25], v[64:79]
	v_add_f32_e32 v6, v8, v6
	v_add_f32_e32 v7, v9, v7
	v_add_f32_e32 v8, v20, v100
	v_add_f32_e32 v9, v21, v101
	v_add_f32_e32 v6, v8, v6
	v_add_f32_e32 v7, v9, v7
	v_add_f32_e32 v8, v52, v102
	v_add_f32_e32 v9, v53, v103
	s_nop 0
	v_add_f32_e32 v6, v8, v6
	v_add_f32_e32 v7, v9, v7
	v_add_f32_e32 v8, v104, v30
	v_add_f32_e32 v9, v105, v31
	s_nop 0
	v_add_f32_e32 v6, v8, v6
	v_add_f32_e32 v7, v9, v7
	s_nop 0
	v_add_f32_e32 v216, v6, v7
	v_add_f32_e32 v216, v216, v215
	s_cmp_lg_u32 s99, 0
	s_cbranch_scc1 .Latt_slow2A
.Latt_cont2A:
	s_branch .Latt_barA
.Latt_slowA:
	v_max_f32_e32 v10, v0, v206
	v_mov_b32_e32 v206, 0
	v_mov_b32_e32 v208, 0
	v_mov_b32_e32 v234, v10
	s_mov_b32 s99, 1
	v_sub_f32_e32 v16, v16, v10
	v_sub_f32_e32 v17, v17, v10
	v_sub_f32_e32 v18, v18, v10
	v_sub_f32_e32 v19, v19, v10
	v_sub_f32_e32 v20, v20, v10
	v_sub_f32_e32 v21, v21, v10
	v_sub_f32_e32 v22, v22, v10
	v_sub_f32_e32 v23, v23, v10
	v_sub_f32_e32 v24, v24, v10
	v_sub_f32_e32 v25, v25, v10
	v_sub_f32_e32 v26, v26, v10
	v_sub_f32_e32 v27, v27, v10
	v_sub_f32_e32 v28, v28, v10
	v_sub_f32_e32 v29, v29, v10
	v_sub_f32_e32 v30, v30, v10
	v_sub_f32_e32 v31, v31, v10
	v_sub_f32_e32 v48, v48, v10
	v_sub_f32_e32 v49, v49, v10
	v_sub_f32_e32 v50, v50, v10
	v_sub_f32_e32 v51, v51, v10
	v_sub_f32_e32 v52, v52, v10
	v_sub_f32_e32 v53, v53, v10
	v_sub_f32_e32 v54, v54, v10
	v_sub_f32_e32 v55, v55, v10
	v_sub_f32_e32 v56, v56, v10
	v_sub_f32_e32 v57, v57, v10
	v_sub_f32_e32 v58, v58, v10
	v_sub_f32_e32 v59, v59, v10
	v_sub_f32_e32 v60, v60, v10
	v_sub_f32_e32 v61, v61, v10
	v_sub_f32_e32 v62, v62, v10
	v_sub_f32_e32 v63, v63, v10
	v_sub_f32_e32 v11, 0, v10
	v_min_f32_e32 v11, 0x42fc0000, v11
	v_exp_f32_e32 v11, v11
	s_nop 0
	v_mul_f32_e32 v32, v32, v11
	v_mul_f32_e32 v33, v33, v11
	v_mul_f32_e32 v34, v34, v11
	v_mul_f32_e32 v35, v35, v11
	v_mul_f32_e32 v36, v36, v11
	v_mul_f32_e32 v37, v37, v11
	v_mul_f32_e32 v38, v38, v11
	v_mul_f32_e32 v39, v39, v11
	v_mul_f32_e32 v40, v40, v11
	v_mul_f32_e32 v41, v41, v11
	v_mul_f32_e32 v42, v42, v11
	v_mul_f32_e32 v43, v43, v11
	v_mul_f32_e32 v44, v44, v11
	v_mul_f32_e32 v45, v45, v11
	v_mul_f32_e32 v46, v46, v11
	v_mul_f32_e32 v47, v47, v11
	v_mul_f32_e32 v64, v64, v11
	v_mul_f32_e32 v65, v65, v11
	v_mul_f32_e32 v66, v66, v11
	v_mul_f32_e32 v67, v67, v11
	v_mul_f32_e32 v68, v68, v11
	v_mul_f32_e32 v69, v69, v11
	v_mul_f32_e32 v70, v70, v11
	v_mul_f32_e32 v71, v71, v11
	v_mul_f32_e32 v72, v72, v11
	v_mul_f32_e32 v73, v73, v11
	v_mul_f32_e32 v74, v74, v11
	v_mul_f32_e32 v75, v75, v11
	v_mul_f32_e32 v76, v76, v11
	v_mul_f32_e32 v77, v77, v11
	v_mul_f32_e32 v78, v78, v11
	v_mul_f32_e32 v79, v79, v11
	v_mul_f32_e32 v215, v215, v11
	s_nop 1
	s_branch .Latt_contA

; #define LAS __attribute__((address_space(3)))
; template <bool QK, bool SM>
; __device__ __forceinline__ void attn_step(const LAS unsigned char* kb, const LAS unsigned char* vbp, const bf16x8 (&qr)[6],
;                                           f32x16& s0, f32x16& s1, f32x16& o0, f32x16& o1, float& mrow, float& lsum) {
;     ...
;         for (int s = 0; s < 6; ++s) { const bf16x8 ka = *(const LAS bf16x8*)(kb + s * 32), kc = *(const LAS bf16x8*)(kb + 32 * KPITCH + s * 32);
;             n0 = __builtin_amdgcn_mfma_f32_32x32x16_bf16(ka, qr[s], n0, 0, 0, 0); n1 = __builtin_amdgcn_mfma_f32_32x32x16_bf16(kc, qr[s], n1, 0, 0, 0); }
;     ...
;         for (int r = 0; r < 16; r += 2) { f32x2 a = (f32x2){s0[r], s0[r + 1]} - m2, b = (f32x2){s1[r], s1[r + 1]} - m2;
;             a.x = __builtin_amdgcn_exp2f(a.x); a.y = __builtin_amdgcn_exp2f(a.y); b.x = __builtin_amdgcn_exp2f(b.x); b.y = __builtin_amdgcn_exp2f(b.y);
;             s0[r] = a.x; s0[r + 1] = a.y; s1[r] = b.x; s1[r + 1] = b.y; ps2 += a + b; }
.Latt_contB:
	s_waitcnt lgkmcnt(3)
	v_mfma_f32_32x32x16_bf16 v[48:63], v[26:29], v[148:151], v[48:63]
	v_exp_f32_e32 v130, v114
	v_exp_f32_e32 v131, v115
	v_exp_f32_e32 v114, v82
	v_exp_f32_e32 v115, v83
	v_mfma_f32_32x32x16_bf16 v[16:31], v[14:17], v[164:167], v[218:233]
	v_exp_f32_e32 v128, v112
	v_exp_f32_e32 v129, v113
	v_exp_f32_e32 v112, v80
	v_exp_f32_e32 v113, v81
	v_add_f32_e32 v12, v130, v114
	v_add_f32_e32 v13, v131, v115
	v_mov_b32_e32 v14, v84
	v_mov_b32_e32 v15, v85
	v_mfma_f32_32x32x16_bf16 v[16:31], v[96:99], v[160:163], v[16:31]
	v_add_f32_e32 v10, v128, v112
	v_add_f32_e32 v11, v129, v113
	v_exp_f32_e32 v80, v118
	v_exp_f32_e32 v81, v119
	v_add_f32_e32 v10, 0, v10
	v_add_f32_e32 v11, 0, v11
	v_exp_f32_e32 v82, v120
	v_mfma_f32_32x32x16_bf16 v[16:31], v[100:103], v[156:159], v[16:31]
	v_exp_f32_e32 v83, v121
	v_add_f32_e32 v10, v12, v10
	v_add_f32_e32 v11, v13, v11
	v_exp_f32_e32 v84, v122
	v_exp_f32_e32 v85, v123
	v_mfma_f32_32x32x16_bf16 v[16:31], v[104:107], v[152:155], v[16:31]
	v_mov_b32_e32 v12, v116
	v_mov_b32_e32 v13, v117
	v_exp_f32_e32 v116, v124
	v_exp_f32_e32 v117, v125
	s_waitcnt lgkmcnt(2)
	v_mfma_f32_32x32x16_bf16 v[48:63], v[108:111], v[144:147], v[48:63]
	v_add_u32_e32 v110, 0x8800, v132
	v_add_u32_e32 v111, 0x9800, v132
	ds_read2_b64 v[100:103], v111 offset0:96 offset1:98
	v_exp_f32_e32 v12, v12
	s_waitcnt lgkmcnt(2)
	v_mfma_f32_32x32x16_bf16 v[16:31], v[6:9], v[148:151], v[16:31]
	ds_read2_b64 v[6:9], v110 offset0:64 offset1:66
	v_exp_f32_e32 v13, v13

; __device__ __forceinline__ unsigned cvt_pk_bf16(float lo, float hi) { unsigned r; asm("v_cvt_pk_bf16_f32 %0, %1, %2" : "=v"(r) : "v"(lo), "v"(hi)); return r; }
; template <bool QK, bool SM>
; __device__ __forceinline__ void attn_step(const LAS unsigned char* kb, const LAS unsigned char* vbp, const bf16x8 (&qr)[6],
;                                           f32x16& s0, f32x16& s1, f32x16& o0, f32x16& o1, float& mrow, float& lsum) {
;     ...
;         for (int S = 0; S < 4; ++S) { u32x4 w;
;             if (S < 2) { w.x = cvt_pk_bf16(s0[8 * S + 0], s0[8 * S + 1]); w.y = cvt_pk_bf16(s0[8 * S + 2], s0[8 * S + 3]); w.z = cvt_pk_bf16(s0[8 * S + 4], s0[8 * S + 5]); w.w = cvt_pk_bf16(s0[8 * S + 6], s0[8 * S + 7]); }
;             else { w.x = cvt_pk_bf16(s1[8 * S - 16], s1[8 * S - 15]); w.y = cvt_pk_bf16(s1[8 * S - 14], s1[8 * S - 13]); w.z = cvt_pk_bf16(s1[8 * S - 12], s1[8 * S - 11]); w.w = cvt_pk_bf16(s1[8 * S - 10], s1[8 * S - 9]); }
;             pb[S] = __builtin_bit_cast(bf16x8, w); }
	v_cvt_pk_bf16_f32 v96, v128, v129


; __device__ __forceinline__ unsigned cvt_pk_bf16(float lo, float hi) { unsigned r; asm("v_cvt_pk_bf16_f32 %0, %1, %2" : "=v"(r) : "v"(lo), "v"(hi)); return r; }
; template <bool QK, bool SM>
; __device__ __forceinline__ void attn_step(const LAS unsigned char* kb, const LAS unsigned char* vbp, const bf16x8 (&qr)[6],
;                                           f32x16& s0, f32x16& s1, f32x16& o0, f32x16& o1, float& mrow, float& lsum) {
;     ...
;         for (int S = 0; S < 4; ++S) { u32x4 w;
;             if (S < 2) { w.x = cvt_pk_bf16(s0[8 * S + 0], s0[8 * S + 1]); w.y = cvt_pk_bf16(s0[8 * S + 2], s0[8 * S + 3]); w.z = cvt_pk_bf16(s0[8 * S + 4], s0[8 * S + 5]); w.w = cvt_pk_bf16(s0[8 * S + 6], s0[8 * S + 7]); }
;             else { w.x = cvt_pk_bf16(s1[8 * S - 16], s1[8 * S - 15]); w.y = cvt_pk_bf16(s1[8 * S - 14], s1[8 * S - 13]); w.z = cvt_pk_bf16(s1[8 * S - 12], s1[8 * S - 11]); w.w = cvt_pk_bf16(s1[8 * S - 10], s1[8 * S - 9]); }
;             pb[S] = __builtin_bit_cast(bf16x8, w); }
	v_cvt_pk_bf16_f32 v97, v130, v131


; __device__ __forceinline__ unsigned cvt_pk_bf16(float lo, float hi) { unsigned r; asm("v_cvt_pk_bf16_f32 %0, %1, %2" : "=v"(r) : "v"(lo), "v"(hi)); return r; }
; template <bool QK, bool SM>
; __device__ __forceinline__ void attn_step(const LAS unsigned char* kb, const LAS unsigned char* vbp, const bf16x8 (&qr)[6],
;                                           f32x16& s0, f32x16& s1, f32x16& o0, f32x16& o1, float& mrow, float& lsum) {
;     ...
;         for (int S = 0; S < 4; ++S) { u32x4 w;
;             if (S < 2) { w.x = cvt_pk_bf16(s0[8 * S + 0], s0[8 * S + 1]); w.y = cvt_pk_bf16(s0[8 * S + 2], s0[8 * S + 3]); w.z = cvt_pk_bf16(s0[8 * S + 4], s0[8 * S + 5]); w.w = cvt_pk_bf16(s0[8 * S + 6], s0[8 * S + 7]); }
;             else { w.x = cvt_pk_bf16(s1[8 * S - 16], s1[8 * S - 15]); w.y = cvt_pk_bf16(s1[8 * S - 14], s1[8 * S - 13]); w.z = cvt_pk_bf16(s1[8 * S - 12], s1[8 * S - 11]); w.w = cvt_pk_bf16(s1[8 * S - 10], s1[8 * S - 9]); }
;             pb[S] = __builtin_bit_cast(bf16x8, w); }
	v_cvt_pk_bf16_f32 v98, v12, v13


; __device__ __forceinline__ unsigned cvt_pk_bf16(float lo, float hi) { unsigned r; asm("v_cvt_pk_bf16_f32 %0, %1, %2" : "=v"(r) : "v"(lo), "v"(hi)); return r; }
; template <bool QK, bool SM>
; __device__ __forceinline__ void attn_step(const LAS unsigned char* kb, const LAS unsigned char* vbp, const bf16x8 (&qr)[6],
;                                           f32x16& s0, f32x16& s1, f32x16& o0, f32x16& o1, float& mrow, float& lsum) {
;     ...
;         for (int S = 0; S < 4; ++S) { u32x4 w;
;             if (S < 2) { w.x = cvt_pk_bf16(s0[8 * S + 0], s0[8 * S + 1]); w.y = cvt_pk_bf16(s0[8 * S + 2], s0[8 * S + 3]); w.z = cvt_pk_bf16(s0[8 * S + 4], s0[8 * S + 5]); w.w = cvt_pk_bf16(s0[8 * S + 6], s0[8 * S + 7]); }
;             else { w.x = cvt_pk_bf16(s1[8 * S - 16], s1[8 * S - 15]); w.y = cvt_pk_bf16(s1[8 * S - 14], s1[8 * S - 13]); w.z = cvt_pk_bf16(s1[8 * S - 12], s1[8 * S - 11]); w.w = cvt_pk_bf16(s1[8 * S - 10], s1[8 * S - 9]); }
;             pb[S] = __builtin_bit_cast(bf16x8, w); }
	v_cvt_pk_bf16_f32 v99, v80, v81

; #define LAS __attribute__((address_space(3)))
; template <bool QK, bool SM>
; __device__ __forceinline__ void attn_step(const LAS unsigned char* kb, const LAS unsigned char* vbp, const bf16x8 (&qr)[6],
;                                           f32x16& s0, f32x16& s1, f32x16& o0, f32x16& o1, float& mrow, float& lsum) {
;     ...
;         for (int S = 0; S < 4; ++S) {
;             const u32x2 a0 = *(const LAS u32x2*)(vbp + S * 32), a1 = *(const LAS u32x2*)(vbp + S * 32 + 16);
;             const u32x2 c0 = *(const LAS u32x2*)(vbp + 32 * VPITCH + S * 32), c1 = *(const LAS u32x2*)(vbp + 32 * VPITCH + S * 32 + 16);
;             const bf16x8 va = __builtin_bit_cast(bf16x8, (u32x4){a0.x, a0.y, a1.x, a1.y}), vc = __builtin_bit_cast(bf16x8, (u32x4){c0.x, c0.y, c1.x, c1.y});
;             o0 = __builtin_amdgcn_mfma_f32_32x32x16_bf16(va, pb[S], o0, 0, 0, 0); o1 = __builtin_amdgcn_mfma_f32_32x32x16_bf16(vc, pb[S], o1, 0, 0, 0); }
	s_waitcnt lgkmcnt(0)
	s_nop 0
	s_waitcnt vmcnt(5)
	ds_write_b128 v197, v[184:187] offset:13312
	s_and_saveexec_b64 s[10:11], s[0:1]
	s_waitcnt vmcnt(4)
	ds_write_b128 v212, v[180:183] offset:13312
	s_or_b64 exec, exec, s[10:11]
	s_waitcnt vmcnt(3)
	ds_write2_b64 v205, v[188:189], v[190:191] offset1:1
	v_mfma_f32_32x32x16_bf16 v[32:47], v[6:9], v[96:99], v[32:47]
	ds_read2_b64 v[6:9], v110 offset0:68 offset1:70
	v_exp_f32_e32 v14, v14
	v_mfma_f32_32x32x16_bf16 v[64:79], v[100:103], v[96:99], v[64:79]
	ds_read2_b64 v[100:103], v111 offset0:100 offset1:102
	v_exp_f32_e32 v104, v126
	v_exp_f32_e32 v105, v127
	v_cvt_pk_bf16_f32 v96, v82, v83
	v_cvt_pk_bf16_f32 v97, v84, v85
	v_cvt_pk_bf16_f32 v98, v116, v117
	v_cvt_pk_bf16_f32 v99, v104, v105
	v_exp_f32_e32 v15, v15
	s_waitcnt lgkmcnt(1)
	v_mfma_f32_32x32x16_bf16 v[32:47], v[6:9], v[96:99], v[32:47]
	v_exp_f32_e32 v106, v86
	v_exp_f32_e32 v107, v87
	ds_read2_b64 v[6:9], v110 offset0:72 offset1:74
	v_exp_f32_e32 v108, v88
	v_exp_f32_e32 v109, v89
	s_waitcnt lgkmcnt(1)
	v_mfma_f32_32x32x16_bf16 v[64:79], v[100:103], v[96:99], v[64:79]
	ds_read2_b64 v[96:99], v111 offset0:104 offset1:106
	v_cvt_pk_bf16_f32 v86, v112, v113
	v_cvt_pk_bf16_f32 v87, v114, v115
	v_cvt_pk_bf16_f32 v88, v14, v15
	v_cvt_pk_bf16_f32 v89, v106, v107
	s_waitcnt lgkmcnt(1)
	s_nop 0
	v_mfma_f32_32x32x16_bf16 v[32:47], v[6:9], v[86:89], v[32:47]
	v_exp_f32_e32 v100, v90
	v_exp_f32_e32 v101, v91
	v_exp_f32_e32 v102, v92
	v_exp_f32_e32 v103, v93
	ds_read2_b64 v[6:9], v110 offset0:76 offset1:78
	v_exp_f32_e32 v94, v94
	v_exp_f32_e32 v95, v95
	ds_read2_b64 v[90:93], v111 offset0:108 offset1:110
	s_waitcnt lgkmcnt(2)
	v_mfma_f32_32x32x16_bf16 v[64:79], v[96:99], v[86:89], v[64:79]
	v_cvt_pk_bf16_f32 v86, v108, v109
	v_cvt_pk_bf16_f32 v87, v100, v101
	v_cvt_pk_bf16_f32 v88, v102, v103
	v_cvt_pk_bf16_f32 v89, v94, v95
	s_waitcnt lgkmcnt(1)
	s_nop 0
	v_mfma_f32_32x32x16_bf16 v[32:47], v[6:9], v[86:89], v[32:47]
	v_add_f32_e32 v6, v12, v14
	v_add_f32_e32 v7, v13, v15
	v_add_f32_e32 v8, v80, v106
	v_add_f32_e32 v9, v81, v107
	v_add_f32_e32 v6, v6, v10
	v_add_f32_e32 v7, v7, v11
	v_add_f32_e32 v6, v8, v6
	v_add_f32_e32 v7, v9, v7
	v_add_f32_e32 v8, v82, v108
	v_add_f32_e32 v9, v83, v109
	s_waitcnt lgkmcnt(0)
	v_mfma_f32_32x32x16_bf16 v[64:79], v[90:93], v[86:89], v[64:79]
	v_add_f32_e32 v6, v8, v6
	v_add_f32_e32 v7, v9, v7
	v_add_f32_e32 v8, v84, v100
	v_add_f32_e32 v9, v85, v101
	v_add_f32_e32 v6, v8, v6
	v_add_f32_e32 v7, v9, v7
	v_add_f32_e32 v8, v116, v102
	v_add_f32_e32 v9, v117, v103
	s_nop 0
	v_add_f32_e32 v6, v8, v6
	v_add_f32_e32 v7, v9, v7
	v_mfma_f32_32x32x16_bf16 v[16:31], v[2:5], v[144:147], v[16:31]
	v_add_f32_e32 v8, v104, v94
	v_add_f32_e32 v9, v105, v95
	v_add_f32_e32 v6, v8, v6
	v_add_f32_e32 v7, v9, v7
	v_add_f32_e32 v215, v6, v7
	v_add_f32_e32 v215, v215, v216
	s_cmp_lg_u32 s99, 0
	s_cbranch_scc1 .Latt_slow2B
.Latt_cont2B:
	s_branch .Latt_barB
.LBB0_958:
	s_waitcnt vmcnt(4)
	ds_write_b128 v212, v[180:183] offset:13312
	s_branch .LBB0_940
